# NSA output gate chain: removed the second form of dead v_div_scale and its wait state (28 sites)
# baseline (speedup 1.0000x reference)
; #define LAS __attribute__((address_space(3)))
; DI float bflo(unsigned w) { return __uint_as_float(w << 16); }
; DI float bfhi(unsigned w) { return __uint_as_float(w & 0xffff0000u); }
; DI void branch_fold(ASt& st, float gate, bool may_be_empty, LAS float* wsf, int lane) {
;     ...
;     for (int g4 = 0; g4 < 4; ++g4) { const f32x4 f = *(const LAS f32x4*)(wsf + 8 * g4 + 4 * hi);
; #pragma unroll
;         for (int k = 0; k < 4; ++k) { st.o0[4 * g4 + k] *= f[k]; st.o1[4 * g4 + k] *= f[k]; } }
; DI void nsa_unit(const Ctx& c0, int b, int g, int i, LAS unsigned char* lds) {
;     ...
;         branch_fold(st, g_w2, false, wsf, lane);
; #pragma unroll
;         for (int rg = 0; rg < 16; ++rg) { const unsigned w = OC[rg * 64]; ca0[rg] = (OACC[rg * 64] + st.o0[rg]) + bflo(w); ca1[rg] = (OACC[(16 + rg) * 64] + st.o1[rg]) + bfhi(w); }
;         __syncthreads();
;     }
;     ...
;     { const size_t g0 = ((size_t)b * SEQ + i * 64 + 32 * qh) * 512 + head * 64;
;       const bf16* nzg = (const bf16*)(c.ws + O_NZ) + g0; bf16* ong = (bf16*)(c.ws + O_ONSA) + g0;
;       LAS unsigned char* S = lds + A_OC + wid * 4096;
; #pragma unroll
;       for (int it = 0; it < 4; ++it) { const int rw = 8 * it + (lane >> 3), ch = lane & 7;
;           *(LAS u32x4*)(S + rw * 128 + ch * 16) = *(const u32x4*)(nzg + (size_t)rw * 512 + ch * 8); }
.LBB0_540:
	s_or_b64 exec, exec, s[12:13]
	s_or_b32 s3, s24, s33
	s_add_u32 s12, s8, s3
	s_addc_u32 s13, s9, 0
	s_lshl_b64 s[12:13], s[12:13], 9
	s_add_u32 s12, s12, s20
	s_addc_u32 s13, s13, 0
	s_lshl_b64 s[12:13], s[12:13], 1
	s_add_u32 s0, s0, s12
	s_addc_u32 s1, s1, s13
	v_mov_b32_e32 v135, v3
	v_lshl_add_u64 v[246:247], s[0:1], 0, v[134:135]
	s_mov_b64 s[98:99], 0xb500000
	v_lshl_add_u64 v[246:247], v[246:247], 0, s[98:99]
	v_lshl_add_u64 v[248:249], v[246:247], 0, v[126:127]
	global_load_dwordx4 v[230:233], v[248:249], off
	v_lshl_add_u64 v[248:249], v[246:247], 0, v[128:129]
	global_load_dwordx4 v[234:237], v[248:249], off
	v_lshl_add_u64 v[248:249], v[246:247], 0, v[130:131]
	global_load_dwordx4 v[238:241], v[248:249], off
	v_lshl_add_u64 v[248:249], v[246:247], 0, v[132:133]
	global_load_dwordx4 v[242:245], v[248:249], off
	s_waitcnt lgkmcnt(0)
	ds_read_b128 v[48:51], v205 offset:32768
	ds_read_b128 v[44:47], v205 offset:32800
	ds_read_b128 v[40:43], v205 offset:32832
	ds_read_b128 v[36:39], v205 offset:32864
	ds_read2st64_b32 v[52:53], v203 offset1:1
	ds_read2st64_b32 v[54:55], v214 offset0:144 offset1:145
	ds_read2st64_b32 v[56:57], v214 offset0:160 offset1:161
	s_waitcnt lgkmcnt(0)
	v_lshlrev_b32_e32 v2, 16, v52
	v_fma_f32 v1, v20, v48, v54
	v_add_f32_e32 v60, v1, v2
	v_fma_f32 v1, v4, v48, v56
	v_fmac_f32_e32 v55, v21, v49
	v_fmac_f32_e32 v57, v5, v49
	ds_read2st64_b32 v[4:5], v203 offset0:2 offset1:3
	ds_read2st64_b32 v[20:21], v214 offset0:146 offset1:147
	ds_read2st64_b32 v[48:49], v214 offset0:162 offset1:163
	v_and_b32_e32 v2, 0xffff0000, v52
	v_add_f32_e32 v59, v1, v2
	v_lshlrev_b32_e32 v1, 16, v53
	v_add_f32_e32 v58, v55, v1
	v_and_b32_e32 v1, 0xffff0000, v53
	v_add_f32_e32 v57, v57, v1
	s_waitcnt lgkmcnt(0)
	v_fma_f32 v1, v22, v50, v20
	v_lshlrev_b32_e32 v2, 16, v4
	v_add_f32_e32 v56, v1, v2
	v_fma_f32 v1, v6, v50, v48
	v_and_b32_e32 v2, 0xffff0000, v4
	v_add_f32_e32 v55, v1, v2
	v_fmac_f32_e32 v21, v23, v51
	v_lshlrev_b32_e32 v1, 16, v5
	v_add_f32_e32 v54, v21, v1
	v_fmac_f32_e32 v49, v7, v51
	v_and_b32_e32 v1, 0xffff0000, v5
	ds_read2st64_b32 v[4:5], v203 offset0:4 offset1:5
	ds_read2st64_b32 v[6:7], v214 offset0:148 offset1:149
	ds_read2st64_b32 v[20:21], v214 offset0:164 offset1:165
	v_add_f32_e32 v53, v49, v1
	s_waitcnt lgkmcnt(0)
	v_lshlrev_b32_e32 v2, 16, v4
	v_fma_f32 v1, v24, v44, v6
	v_add_f32_e32 v52, v1, v2
	v_fma_f32 v1, v8, v44, v20
	v_and_b32_e32 v2, 0xffff0000, v4
	v_add_f32_e32 v51, v1, v2
	v_fmac_f32_e32 v7, v25, v45
	v_lshlrev_b32_e32 v1, 16, v5
	v_add_f32_e32 v50, v7, v1
	v_and_b32_e32 v1, 0xffff0000, v5
	ds_read2st64_b32 v[4:5], v203 offset0:6 offset1:7
	ds_read2st64_b32 v[6:7], v214 offset0:150 offset1:151
	v_fmac_f32_e32 v21, v9, v45
	ds_read2st64_b32 v[8:9], v214 offset0:166 offset1:167
	v_add_f32_e32 v49, v21, v1
	s_waitcnt lgkmcnt(0)
	v_lshlrev_b32_e32 v2, 16, v4
	v_fma_f32 v1, v26, v46, v6
	v_add_f32_e32 v48, v1, v2
	v_fma_f32 v1, v10, v46, v8
	v_and_b32_e32 v2, 0xffff0000, v4
	v_add_f32_e32 v46, v1, v2
	v_fmac_f32_e32 v7, v27, v47
	v_lshlrev_b32_e32 v1, 16, v5
	v_add_f32_e32 v45, v7, v1
	v_fmac_f32_e32 v9, v11, v47
	v_and_b32_e32 v1, 0xffff0000, v5
	ds_read2st64_b32 v[4:5], v203 offset0:8 offset1:9
	ds_read2st64_b32 v[6:7], v214 offset0:152 offset1:153
	v_add_f32_e32 v44, v9, v1
	ds_read2st64_b32 v[8:9], v214 offset0:168 offset1:169
	s_waitcnt lgkmcnt(0)
	v_lshlrev_b32_e32 v2, 16, v4
	v_fma_f32 v1, v28, v40, v6
	v_add_f32_e32 v27, v1, v2
	v_fma_f32 v1, v12, v40, v8
	v_and_b32_e32 v2, 0xffff0000, v4
	v_add_f32_e32 v26, v1, v2
	v_fmac_f32_e32 v7, v29, v41
	v_lshlrev_b32_e32 v1, 16, v5
	v_add_f32_e32 v25, v7, v1
	v_fmac_f32_e32 v9, v13, v41
	v_and_b32_e32 v1, 0xffff0000, v5
	ds_read2st64_b32 v[4:5], v203 offset0:10 offset1:11
	ds_read2st64_b32 v[6:7], v214 offset0:154 offset1:155
	v_add_f32_e32 v24, v9, v1
	ds_read2st64_b32 v[8:9], v214 offset0:170 offset1:171
	s_waitcnt lgkmcnt(0)
	v_lshlrev_b32_e32 v2, 16, v4
	v_fma_f32 v1, v30, v42, v6
	v_add_f32_e32 v23, v1, v2
	v_fma_f32 v1, v14, v42, v8
	v_and_b32_e32 v2, 0xffff0000, v4
	v_add_f32_e32 v22, v1, v2
	v_fmac_f32_e32 v7, v31, v43
	v_lshlrev_b32_e32 v1, 16, v5
	v_add_f32_e32 v21, v7, v1
	v_fmac_f32_e32 v9, v15, v43
	v_and_b32_e32 v1, 0xffff0000, v5
	ds_read2st64_b32 v[4:5], v203 offset0:12 offset1:13
	ds_read2st64_b32 v[6:7], v214 offset0:156 offset1:157
	v_add_f32_e32 v15, v9, v1
	ds_read2st64_b32 v[8:9], v214 offset0:172 offset1:173
	s_waitcnt lgkmcnt(0)
	v_lshlrev_b32_e32 v2, 16, v4
	v_fma_f32 v1, v32, v36, v6
	v_add_f32_e32 v20, v1, v2
	v_fma_f32 v1, v16, v36, v8
	v_and_b32_e32 v2, 0xffff0000, v4
	v_add_f32_e32 v14, v1, v2
	v_fmac_f32_e32 v7, v33, v37
	v_lshlrev_b32_e32 v1, 16, v5
	v_add_f32_e32 v13, v7, v1
	v_fmac_f32_e32 v9, v17, v37
	v_and_b32_e32 v1, 0xffff0000, v5
	ds_read2st64_b32 v[4:5], v203 offset0:14 offset1:15
	ds_read2st64_b32 v[6:7], v214 offset0:158 offset1:159
	v_add_f32_e32 v12, v9, v1
	ds_read2st64_b32 v[8:9], v214 offset0:174 offset1:175
	s_waitcnt lgkmcnt(0)
	v_lshlrev_b32_e32 v2, 16, v4
	v_fma_f32 v1, v34, v38, v6
	v_add_f32_e32 v10, v1, v2
	v_fma_f32 v1, v18, v38, v8
	v_and_b32_e32 v2, 0xffff0000, v4
	v_add_f32_e32 v11, v1, v2
	v_fmac_f32_e32 v7, v35, v39
	v_lshlrev_b32_e32 v1, 16, v5
	v_add_f32_e32 v2, v7, v1
	v_fmac_f32_e32 v9, v19, v39
	v_and_b32_e32 v1, 0xffff0000, v5
	v_mov_b32_e32 v135, v3
	v_add_f32_e32 v1, v9, v1
	v_lshl_add_u64 v[8:9], s[0:1], 0, v[134:135]
	s_mov_b64 s[0:1], 0xb500000
	v_lshl_add_u64 v[16:17], v[8:9], 0, s[0:1]
	v_lshl_add_u64 v[4:5], v[16:17], 0, v[126:127]
	s_barrier
; #define LAS __attribute__((address_space(3)))
; #define LDS_WAIT() asm volatile("s_waitcnt lgkmcnt(0)" ::: "memory")
; DI unsigned cvtpk(float lo, float hi) { f32x2 v = {lo, hi}; bf16x2_t b = __builtin_convertvector(v, bf16x2_t); return __builtin_bit_cast(unsigned, b); }
; DI float bf2f(bf16 b) { return __uint_as_float(((unsigned)b) << 16); }
; DI float siluf_(float x) { return x / (1.f + __expf(-x)); }
; DI void nsa_unit(const Ctx& c0, int b, int g, int i, LAS unsigned char* lds) {
;     ...
;       for (int it = 0; it < 4; ++it) { const int rw = 8 * it + (lane >> 3), ch = lane & 7;
;           *(LAS u32x4*)(S + rw * 128 + ch * 16) = *(const u32x4*)(nzg + (size_t)rw * 512 + ch * 8); }
;       LDS_WAIT();
; #pragma unroll
;       for (int rg = 0; rg < 16; ++rg) { LAS bf16* e = (LAS bf16*)(S + ((rg & 3) + 8 * (rg >> 2) + 4 * hi) * 128 + r * 2);
;           const float z0 = bf2f(e[0]), z1 = bf2f(e[32]);
;           e[0] = (bf16)(cvtpk(ca0[rg] * siluf_(z0), 0.f) & 0xffffu);
;           e[32] = (bf16)(cvtpk(ca1[rg] * siluf_(z1), 0.f) & 0xffffu); }
	s_add_i32 s23, s23, 1
	s_cmp_eq_u32 s23, 4
	s_waitcnt vmcnt(0) lgkmcnt(0)
	ds_write_b128 v216, v[230:233]
	ds_write_b128 v217, v[234:237]
	ds_write_b128 v218, v[238:241]
	ds_write_b128 v219, v[242:245]
	s_waitcnt lgkmcnt(0)
	ds_read_u16 v4, v220
	ds_read_u16 v5, v220 offset:64
	s_waitcnt lgkmcnt(1)
	v_lshlrev_b32_e32 v4, 16, v4
	v_mul_f32_e32 v6, 0xbfb8aa3b, v4
	v_exp_f32_e32 v6, v6
	s_waitcnt lgkmcnt(0)
	v_lshlrev_b32_e32 v5, 16, v5
	v_add_f32_e32 v6, 1.0, v6
	v_rcp_f32_e32 v7, v6
	s_nop 0
	v_mul_f32_e32 v4, v4, v7
	v_mul_f32_e32 v4, v60, v4
	v_cvt_pk_bf16_f32 v4, v4, v4
	ds_write_b16 v220, v4
	v_mul_f32_e32 v4, 0xbfb8aa3b, v5
	v_exp_f32_e32 v4, v4
	s_nop 0
	v_add_f32_e32 v4, 1.0, v4
	v_rcp_f32_e32 v4, v4
	s_nop 0
	v_mul_f32_e32 v4, v5, v4
	v_mul_f32_e32 v4, v59, v4
	v_cvt_pk_bf16_f32 v4, v4, v4
	ds_write_b16 v220, v4 offset:64
	ds_read_u16 v4, v220 offset:128
	ds_read_u16 v5, v220 offset:192
	s_waitcnt lgkmcnt(1)
	v_lshlrev_b32_e32 v4, 16, v4
	v_mul_f32_e32 v6, 0xbfb8aa3b, v4
	v_exp_f32_e32 v6, v6
	s_waitcnt lgkmcnt(0)
	v_lshlrev_b32_e32 v5, 16, v5
	v_add_f32_e32 v6, 1.0, v6
	v_rcp_f32_e32 v7, v6
	s_nop 0
	v_mul_f32_e32 v4, v4, v7
	v_mul_f32_e32 v4, v58, v4
	v_cvt_pk_bf16_f32 v4, v4, v4
	ds_write_b16 v220, v4 offset:128
	v_mul_f32_e32 v4, 0xbfb8aa3b, v5
	v_exp_f32_e32 v4, v4
	s_nop 0
	v_add_f32_e32 v4, 1.0, v4
	v_rcp_f32_e32 v4, v4
	s_nop 0
	v_mul_f32_e32 v4, v5, v4
	v_mul_f32_e32 v4, v57, v4
	v_cvt_pk_bf16_f32 v4, v4, v4
	ds_write_b16 v220, v4 offset:192
	ds_read_u16 v4, v220 offset:256
	ds_read_u16 v5, v220 offset:320
	s_waitcnt lgkmcnt(1)
	v_lshlrev_b32_e32 v4, 16, v4
	v_mul_f32_e32 v6, 0xbfb8aa3b, v4
	v_exp_f32_e32 v6, v6
	s_waitcnt lgkmcnt(0)
	v_lshlrev_b32_e32 v5, 16, v5
	v_add_f32_e32 v6, 1.0, v6
	v_rcp_f32_e32 v7, v6
	s_nop 0
	v_mul_f32_e32 v4, v4, v7
	v_mul_f32_e32 v4, v56, v4
	v_cvt_pk_bf16_f32 v4, v4, v4
	ds_write_b16 v220, v4 offset:256
	v_mul_f32_e32 v4, 0xbfb8aa3b, v5
	v_exp_f32_e32 v4, v4
	s_nop 0
	v_add_f32_e32 v4, 1.0, v4
	v_rcp_f32_e32 v4, v4
	s_nop 0
	v_mul_f32_e32 v4, v5, v4
	v_mul_f32_e32 v4, v55, v4
	v_cvt_pk_bf16_f32 v4, v4, v4
	ds_write_b16 v220, v4 offset:320
	ds_read_u16 v4, v220 offset:384
	ds_read_u16 v5, v220 offset:448
	s_waitcnt lgkmcnt(1)
	v_lshlrev_b32_e32 v4, 16, v4
	v_mul_f32_e32 v6, 0xbfb8aa3b, v4
	v_exp_f32_e32 v6, v6
	s_waitcnt lgkmcnt(0)
	v_lshlrev_b32_e32 v5, 16, v5
	v_add_f32_e32 v6, 1.0, v6
	v_rcp_f32_e32 v7, v6
	s_nop 0
	v_mul_f32_e32 v4, v4, v7
	v_mul_f32_e32 v4, v54, v4
	v_cvt_pk_bf16_f32 v4, v4, v4
	ds_write_b16 v220, v4 offset:384
	v_mul_f32_e32 v4, 0xbfb8aa3b, v5
	v_exp_f32_e32 v4, v4
	s_nop 0
	v_add_f32_e32 v4, 1.0, v4
	v_rcp_f32_e32 v4, v4
	s_nop 0
	v_mul_f32_e32 v4, v5, v4
	v_mul_f32_e32 v4, v53, v4
	v_cvt_pk_bf16_f32 v4, v4, v4
	ds_write_b16 v220, v4 offset:448
	ds_read_u16 v4, v220 offset:1024
	ds_read_u16 v5, v220 offset:1088
	s_waitcnt lgkmcnt(1)
	v_lshlrev_b32_e32 v4, 16, v4
	v_mul_f32_e32 v6, 0xbfb8aa3b, v4
	v_exp_f32_e32 v6, v6
	s_waitcnt lgkmcnt(0)
	v_lshlrev_b32_e32 v5, 16, v5
	v_add_f32_e32 v6, 1.0, v6
	v_rcp_f32_e32 v7, v6
	s_nop 0
	v_mul_f32_e32 v4, v4, v7
	v_mul_f32_e32 v4, v52, v4
	v_cvt_pk_bf16_f32 v4, v4, v4
	ds_write_b16 v220, v4 offset:1024
	v_mul_f32_e32 v4, 0xbfb8aa3b, v5
	v_exp_f32_e32 v4, v4
	s_nop 0
	v_add_f32_e32 v4, 1.0, v4
	v_rcp_f32_e32 v4, v4
	s_nop 0
	v_mul_f32_e32 v4, v5, v4
	v_mul_f32_e32 v4, v51, v4
	v_cvt_pk_bf16_f32 v4, v4, v4
	ds_write_b16 v220, v4 offset:1088
	ds_read_u16 v4, v220 offset:1152
	ds_read_u16 v5, v220 offset:1216
	s_waitcnt lgkmcnt(1)
	v_lshlrev_b32_e32 v4, 16, v4
	v_mul_f32_e32 v6, 0xbfb8aa3b, v4
	v_exp_f32_e32 v6, v6
	s_waitcnt lgkmcnt(0)
	v_lshlrev_b32_e32 v5, 16, v5
	v_add_f32_e32 v6, 1.0, v6
	v_rcp_f32_e32 v7, v6
	s_nop 0
	v_mul_f32_e32 v4, v4, v7
	v_mul_f32_e32 v4, v50, v4
	v_cvt_pk_bf16_f32 v4, v4, v4
	ds_write_b16 v220, v4 offset:1152
	v_mul_f32_e32 v4, 0xbfb8aa3b, v5
	v_exp_f32_e32 v4, v4
	s_nop 0
	v_add_f32_e32 v4, 1.0, v4
	v_rcp_f32_e32 v4, v4
	s_nop 0
	v_mul_f32_e32 v4, v5, v4
	v_mul_f32_e32 v4, v49, v4
	v_cvt_pk_bf16_f32 v4, v4, v4
	ds_write_b16 v220, v4 offset:1216
	ds_read_u16 v4, v220 offset:1280
	ds_read_u16 v5, v220 offset:1344
	s_waitcnt lgkmcnt(1)
	v_lshlrev_b32_e32 v4, 16, v4
	v_mul_f32_e32 v6, 0xbfb8aa3b, v4
	v_exp_f32_e32 v6, v6
	s_waitcnt lgkmcnt(0)
	v_lshlrev_b32_e32 v5, 16, v5
	v_add_f32_e32 v6, 1.0, v6
	v_rcp_f32_e32 v7, v6
	s_nop 0
	v_mul_f32_e32 v4, v4, v7
	v_mul_f32_e32 v4, v48, v4
	v_cvt_pk_bf16_f32 v4, v4, v4
	ds_write_b16 v220, v4 offset:1280
	v_mul_f32_e32 v4, 0xbfb8aa3b, v5
	v_exp_f32_e32 v4, v4
	s_nop 0
	v_add_f32_e32 v4, 1.0, v4
	v_rcp_f32_e32 v4, v4
	s_nop 0
	v_mul_f32_e32 v4, v5, v4
	v_mul_f32_e32 v4, v46, v4
	v_cvt_pk_bf16_f32 v4, v4, v4
	ds_write_b16 v220, v4 offset:1344
	ds_read_u16 v4, v220 offset:1408
	s_waitcnt lgkmcnt(0)
	v_lshlrev_b32_e32 v5, 16, v4
	v_mul_f32_e32 v6, 0xbfb8aa3b, v5
	v_exp_f32_e32 v6, v6
	ds_read_u16 v4, v220 offset:1472
	v_add_f32_e32 v6, 1.0, v6
	v_div_scale_f32 v7, s[0:1], v6, v6, v5
	s_waitcnt lgkmcnt(0)
	v_lshlrev_b32_e32 v4, 16, v4
	v_rcp_f32_e32 v7, v6
	s_nop 0
	v_mul_f32_e32 v5, v5, v7
	v_mul_f32_e32 v5, v45, v5
	v_cvt_pk_bf16_f32 v5, v5, s0
	ds_write_b16 v220, v5 offset:1408
	v_mul_f32_e32 v5, 0xbfb8aa3b, v4
	v_exp_f32_e32 v5, v5
	s_nop 0
	v_add_f32_e32 v5, 1.0, v5
	v_rcp_f32_e32 v6, v5
	s_nop 0
	v_mul_f32_e32 v4, v4, v6
	v_mul_f32_e32 v4, v44, v4
	v_cvt_pk_bf16_f32 v4, v4, v4
	ds_write_b16 v220, v4 offset:1472
	ds_read_u16 v4, v220 offset:2048
	ds_read_u16 v5, v220 offset:2112
	s_waitcnt lgkmcnt(1)
	v_lshlrev_b32_e32 v4, 16, v4
	v_mul_f32_e32 v6, 0xbfb8aa3b, v4
	v_exp_f32_e32 v6, v6
	s_waitcnt lgkmcnt(0)
; #define LAS __attribute__((address_space(3)))
; #define LDS_WAIT() asm volatile("s_waitcnt lgkmcnt(0)" ::: "memory")
; DI unsigned cvtpk(float lo, float hi) { f32x2 v = {lo, hi}; bf16x2_t b = __builtin_convertvector(v, bf16x2_t); return __builtin_bit_cast(unsigned, b); }
; DI float bf2f(bf16 b) { return __uint_as_float(((unsigned)b) << 16); }
; DI float siluf_(float x) { return x / (1.f + __expf(-x)); }
; DI void nsa_unit(const Ctx& c0, int b, int g, int i, LAS unsigned char* lds) {
;     ...
;       for (int rg = 0; rg < 16; ++rg) { LAS bf16* e = (LAS bf16*)(S + ((rg & 3) + 8 * (rg >> 2) + 4 * hi) * 128 + r * 2);
;           const float z0 = bf2f(e[0]), z1 = bf2f(e[32]);
;           e[0] = (bf16)(cvtpk(ca0[rg] * siluf_(z0), 0.f) & 0xffffu);
;           e[32] = (bf16)(cvtpk(ca1[rg] * siluf_(z1), 0.f) & 0xffffu); }
;       LDS_WAIT();
; #pragma unroll
;       for (int it = 0; it < 4; ++it) { const int rw = 8 * it + (lane >> 3), ch = lane & 7;
;           *(u32x4*)(ong + (size_t)rw * 512 + ch * 8) = *(const LAS u32x4*)(S + rw * 128 + ch * 16); }
;       LDS_WAIT(); }
	v_lshlrev_b32_e32 v5, 16, v5
	v_add_f32_e32 v6, 1.0, v6
	v_rcp_f32_e32 v7, v6
	s_nop 0
	v_mul_f32_e32 v4, v4, v7
	v_mul_f32_e32 v4, v27, v4
	v_cvt_pk_bf16_f32 v4, v4, v4
	ds_write_b16 v220, v4 offset:2048
	v_mul_f32_e32 v4, 0xbfb8aa3b, v5
	v_exp_f32_e32 v4, v4
	s_nop 0
	v_add_f32_e32 v4, 1.0, v4
	v_rcp_f32_e32 v4, v4
	s_nop 0
	v_mul_f32_e32 v4, v5, v4
	v_mul_f32_e32 v4, v26, v4
	v_cvt_pk_bf16_f32 v4, v4, v4
	ds_write_b16 v220, v4 offset:2112
	ds_read_u16 v4, v220 offset:2176
	ds_read_u16 v5, v220 offset:2240
	s_waitcnt lgkmcnt(1)
	v_lshlrev_b32_e32 v4, 16, v4
	v_mul_f32_e32 v6, 0xbfb8aa3b, v4
	v_exp_f32_e32 v6, v6
	s_waitcnt lgkmcnt(0)
	v_lshlrev_b32_e32 v5, 16, v5
	v_add_f32_e32 v6, 1.0, v6
	v_rcp_f32_e32 v7, v6
	s_nop 0
	v_mul_f32_e32 v4, v4, v7
	v_mul_f32_e32 v4, v25, v4
	v_cvt_pk_bf16_f32 v4, v4, v4
	ds_write_b16 v220, v4 offset:2176
	v_mul_f32_e32 v4, 0xbfb8aa3b, v5
	v_exp_f32_e32 v4, v4
	s_nop 0
	v_add_f32_e32 v4, 1.0, v4
	v_rcp_f32_e32 v4, v4
	s_nop 0
	v_mul_f32_e32 v4, v5, v4
	v_mul_f32_e32 v4, v24, v4
	v_cvt_pk_bf16_f32 v4, v4, v4
	ds_write_b16 v220, v4 offset:2240
	ds_read_u16 v4, v220 offset:2304
	ds_read_u16 v5, v220 offset:2368
	s_waitcnt lgkmcnt(1)
	v_lshlrev_b32_e32 v4, 16, v4
	v_mul_f32_e32 v6, 0xbfb8aa3b, v4
	v_exp_f32_e32 v6, v6
	s_waitcnt lgkmcnt(0)
	v_lshlrev_b32_e32 v5, 16, v5
	v_add_f32_e32 v6, 1.0, v6
	v_rcp_f32_e32 v7, v6
	s_nop 0
	v_mul_f32_e32 v4, v4, v7
	v_mul_f32_e32 v4, v23, v4
	v_cvt_pk_bf16_f32 v4, v4, v4
	ds_write_b16 v220, v4 offset:2304
	v_mul_f32_e32 v4, 0xbfb8aa3b, v5
	v_exp_f32_e32 v4, v4
	s_nop 0
	v_add_f32_e32 v4, 1.0, v4
	v_rcp_f32_e32 v4, v4
	s_nop 0
	v_mul_f32_e32 v4, v5, v4
	v_mul_f32_e32 v4, v22, v4
	v_cvt_pk_bf16_f32 v4, v4, v4
	ds_write_b16 v220, v4 offset:2368
	ds_read_u16 v4, v220 offset:2432
	ds_read_u16 v5, v220 offset:2496
	s_waitcnt lgkmcnt(1)
	v_lshlrev_b32_e32 v4, 16, v4
	v_mul_f32_e32 v6, 0xbfb8aa3b, v4
	v_exp_f32_e32 v6, v6
	s_waitcnt lgkmcnt(0)
	v_lshlrev_b32_e32 v5, 16, v5
	v_add_f32_e32 v6, 1.0, v6
	v_rcp_f32_e32 v7, v6
	s_nop 0
	v_mul_f32_e32 v4, v4, v7
	v_mul_f32_e32 v4, v21, v4
	v_cvt_pk_bf16_f32 v4, v4, v4
	ds_write_b16 v220, v4 offset:2432
	v_mul_f32_e32 v4, 0xbfb8aa3b, v5
	v_exp_f32_e32 v4, v4
	s_nop 0
	v_add_f32_e32 v4, 1.0, v4
	v_rcp_f32_e32 v4, v4
	s_nop 0
	v_mul_f32_e32 v4, v5, v4
	v_mul_f32_e32 v4, v15, v4
	v_cvt_pk_bf16_f32 v4, v4, v4
	ds_write_b16 v220, v4 offset:2496
	ds_read_u16 v4, v220 offset:3072
	ds_read_u16 v5, v220 offset:3136
	s_waitcnt lgkmcnt(1)
	v_lshlrev_b32_e32 v4, 16, v4
	v_mul_f32_e32 v6, 0xbfb8aa3b, v4
	v_exp_f32_e32 v6, v6
	s_waitcnt lgkmcnt(0)
	v_lshlrev_b32_e32 v5, 16, v5
	v_add_f32_e32 v6, 1.0, v6
	v_rcp_f32_e32 v7, v6
	s_nop 0
	v_mul_f32_e32 v4, v4, v7
	v_mul_f32_e32 v4, v20, v4
	v_cvt_pk_bf16_f32 v4, v4, v4
	ds_write_b16 v220, v4 offset:3072
	v_mul_f32_e32 v4, 0xbfb8aa3b, v5
	v_exp_f32_e32 v4, v4
	s_nop 0
	v_add_f32_e32 v4, 1.0, v4
	v_rcp_f32_e32 v4, v4
	s_nop 0
	v_mul_f32_e32 v4, v5, v4
	v_mul_f32_e32 v4, v14, v4
	v_cvt_pk_bf16_f32 v4, v4, v4
	ds_write_b16 v220, v4 offset:3136
	ds_read_u16 v4, v220 offset:3200
	ds_read_u16 v5, v220 offset:3264
	s_waitcnt lgkmcnt(1)
	v_lshlrev_b32_e32 v4, 16, v4
	v_mul_f32_e32 v6, 0xbfb8aa3b, v4
	v_exp_f32_e32 v6, v6
	s_waitcnt lgkmcnt(0)
	v_lshlrev_b32_e32 v5, 16, v5
	v_add_f32_e32 v6, 1.0, v6
	v_rcp_f32_e32 v7, v6
	s_nop 0
	v_mul_f32_e32 v4, v4, v7
	v_mul_f32_e32 v4, v13, v4
	v_cvt_pk_bf16_f32 v4, v4, v4
	ds_write_b16 v220, v4 offset:3200
	v_mul_f32_e32 v4, 0xbfb8aa3b, v5
	v_exp_f32_e32 v4, v4
	s_nop 0
	v_add_f32_e32 v4, 1.0, v4
	v_rcp_f32_e32 v4, v4
	s_nop 0
	v_mul_f32_e32 v4, v5, v4
	v_mul_f32_e32 v4, v12, v4
	v_cvt_pk_bf16_f32 v4, v4, v4
	ds_write_b16 v220, v4 offset:3264
	ds_read_u16 v4, v220 offset:3328
	ds_read_u16 v5, v220 offset:3392
	s_waitcnt lgkmcnt(1)
	v_lshlrev_b32_e32 v4, 16, v4
	v_mul_f32_e32 v6, 0xbfb8aa3b, v4
	v_exp_f32_e32 v6, v6
	s_waitcnt lgkmcnt(0)
	v_lshlrev_b32_e32 v5, 16, v5
	v_add_f32_e32 v6, 1.0, v6
	v_rcp_f32_e32 v7, v6
	s_nop 0
	v_mul_f32_e32 v4, v4, v7
	v_mul_f32_e32 v4, v10, v4
	v_cvt_pk_bf16_f32 v4, v4, v4
	ds_write_b16 v220, v4 offset:3328
	v_mul_f32_e32 v4, 0xbfb8aa3b, v5
	v_exp_f32_e32 v4, v4
	s_nop 0
	v_add_f32_e32 v4, 1.0, v4
	v_rcp_f32_e32 v4, v4
	s_nop 0
	v_mul_f32_e32 v4, v5, v4
	v_mul_f32_e32 v4, v11, v4
	v_cvt_pk_bf16_f32 v4, v4, v4
	ds_write_b16 v220, v4 offset:3392
	ds_read_u16 v4, v220 offset:3456
	ds_read_u16 v5, v220 offset:3520
	s_waitcnt lgkmcnt(1)
	v_lshlrev_b32_e32 v4, 16, v4
	v_mul_f32_e32 v6, 0xbfb8aa3b, v4
	v_exp_f32_e32 v6, v6
	s_waitcnt lgkmcnt(0)
	v_lshlrev_b32_e32 v5, 16, v5
	v_add_f32_e32 v6, 1.0, v6
	v_div_scale_f32 v7, s[0:1], v6, v6, v4
	s_nop 0
	v_rcp_f32_e32 v7, v6
	s_nop 0
	v_mul_f32_e32 v4, v4, v7
	v_mul_f32_e32 v2, v2, v4
	v_cvt_pk_bf16_f32 v2, v2, s0
	ds_write_b16 v220, v2 offset:3456
	v_mul_f32_e32 v2, 0xbfb8aa3b, v5
	v_exp_f32_e32 v2, v2
	s_nop 0
	v_add_f32_e32 v2, 1.0, v2
	v_div_scale_f32 v4, s[0:1], v2, v2, v5
	s_nop 0
	v_rcp_f32_e32 v2, v2
	s_nop 0
	v_mul_f32_e32 v2, v5, v2
	v_mul_f32_e32 v1, v1, v2
	v_cvt_pk_bf16_f32 v1, v1, s0
	ds_write_b16 v220, v1 offset:3520
	s_waitcnt lgkmcnt(0)
	ds_read_b128 v[4:7], v216
	s_mov_b64 s[0:1], 0xd500000
	v_lshl_add_u64 v[8:9], v[8:9], 0, s[0:1]
	v_lshl_add_u64 v[10:11], v[8:9], 0, v[126:127]
	s_waitcnt lgkmcnt(0)
	global_store_dwordx4 v[10:11], v[4:7], off
	ds_read_b128 v[4:7], v217
	v_lshl_add_u64 v[10:11], v[8:9], 0, v[128:129]
	s_waitcnt lgkmcnt(0)
	global_store_dwordx4 v[10:11], v[4:7], off
	ds_read_b128 v[4:7], v218
	v_lshl_add_u64 v[10:11], v[8:9], 0, v[130:131]
	v_lshl_add_u64 v[8:9], v[8:9], 0, v[132:133]
	s_waitcnt lgkmcnt(0)
	global_store_dwordx4 v[10:11], v[4:7], off
	ds_read_b128 v[4:7], v219
	s_waitcnt lgkmcnt(0)
	global_store_dwordx4 v[8:9], v[4:7], off
	s_waitcnt lgkmcnt(0)
	s_cbranch_scc1 .LBB0_538

; #define LAS __attribute__((address_space(3)))
; DI float bflo(unsigned w) { return __uint_as_float(w << 16); }
; DI float bfhi(unsigned w) { return __uint_as_float(w & 0xffff0000u); }
; DI void nsa_unit(const Ctx& c0, int b, int g, int i, LAS unsigned char* lds) {
;     ...
;         branch_fold(st, g_w2, false, wsf, lane);
; #pragma unroll
;         for (int rg = 0; rg < 16; ++rg) { const unsigned w = OC[rg * 64]; ca0[rg] = (OACC[rg * 64] + st.o0[rg]) + bflo(w); ca1[rg] = (OACC[(16 + rg) * 64] + st.o1[rg]) + bfhi(w); }
;         __syncthreads();
;     }
;     ...
;     { const size_t g0 = ((size_t)b * SEQ + i * 64 + 32 * qh) * 512 + head * 64;
;       const bf16* nzg = (const bf16*)(c.ws + O_NZ) + g0; bf16* ong = (bf16*)(c.ws + O_ONSA) + g0;
;       LAS unsigned char* S = lds + A_OC + wid * 4096;
; #pragma unroll
;       for (int it = 0; it < 4; ++it) { const int rw = 8 * it + (lane >> 3), ch = lane & 7;
;           *(LAS u32x4*)(S + rw * 128 + ch * 16) = *(const u32x4*)(nzg + (size_t)rw * 512 + ch * 8); }
.LBB0_1153:
	s_or_b64 exec, exec, s[14:15]
	s_or_b32 s6, s26, s33
	s_add_u32 s14, s4, s6
	s_addc_u32 s15, s5, 0
	s_lshl_b64 s[14:15], s[14:15], 9
	s_add_u32 s14, s14, s22
	s_addc_u32 s15, s15, 0
	s_lshl_b64 s[14:15], s[14:15], 1
	s_add_u32 s0, s0, s14
	s_addc_u32 s1, s1, s15
	v_mov_b32_e32 v135, v3
	v_lshl_add_u64 v[246:247], s[0:1], 0, v[134:135]
	s_mov_b64 s[98:99], 0xb500000
	v_lshl_add_u64 v[246:247], v[246:247], 0, s[98:99]
	v_lshl_add_u64 v[248:249], v[246:247], 0, v[126:127]
	global_load_dwordx4 v[230:233], v[248:249], off
	v_lshl_add_u64 v[248:249], v[246:247], 0, v[128:129]
	global_load_dwordx4 v[234:237], v[248:249], off
	v_lshl_add_u64 v[248:249], v[246:247], 0, v[130:131]
	global_load_dwordx4 v[238:241], v[248:249], off
	v_lshl_add_u64 v[248:249], v[246:247], 0, v[132:133]
	global_load_dwordx4 v[242:245], v[248:249], off
	s_waitcnt lgkmcnt(0)
	ds_read_b128 v[48:51], v192 offset:32768
	ds_read_b128 v[44:47], v192 offset:32800
	ds_read_b128 v[40:43], v192 offset:32832
	ds_read_b128 v[36:39], v192 offset:32864
	ds_read2st64_b32 v[52:53], v203 offset1:1
	ds_read2st64_b32 v[54:55], v190 offset0:144 offset1:145
	ds_read2st64_b32 v[56:57], v190 offset0:160 offset1:161
	s_waitcnt lgkmcnt(0)
	v_lshlrev_b32_e32 v2, 16, v52
	v_fma_f32 v1, v20, v48, v54
	v_add_f32_e32 v60, v1, v2
	v_fma_f32 v1, v4, v48, v56
	v_fmac_f32_e32 v55, v21, v49
	v_fmac_f32_e32 v57, v5, v49
	ds_read2st64_b32 v[4:5], v203 offset0:2 offset1:3
	ds_read2st64_b32 v[20:21], v190 offset0:146 offset1:147
	ds_read2st64_b32 v[48:49], v190 offset0:162 offset1:163
	v_and_b32_e32 v2, 0xffff0000, v52
	v_add_f32_e32 v59, v1, v2
	v_lshlrev_b32_e32 v1, 16, v53
	v_add_f32_e32 v58, v55, v1
	v_and_b32_e32 v1, 0xffff0000, v53
	v_add_f32_e32 v57, v57, v1
	s_waitcnt lgkmcnt(0)
	v_fma_f32 v1, v22, v50, v20
	v_lshlrev_b32_e32 v2, 16, v4
	v_add_f32_e32 v56, v1, v2
	v_fma_f32 v1, v6, v50, v48
	v_and_b32_e32 v2, 0xffff0000, v4
	v_add_f32_e32 v55, v1, v2
	v_fmac_f32_e32 v21, v23, v51
	v_lshlrev_b32_e32 v1, 16, v5
	v_add_f32_e32 v54, v21, v1
	v_fmac_f32_e32 v49, v7, v51
	v_and_b32_e32 v1, 0xffff0000, v5
	ds_read2st64_b32 v[4:5], v203 offset0:4 offset1:5
	ds_read2st64_b32 v[6:7], v190 offset0:148 offset1:149
	ds_read2st64_b32 v[20:21], v190 offset0:164 offset1:165
	v_add_f32_e32 v53, v49, v1
	s_waitcnt lgkmcnt(0)
	v_lshlrev_b32_e32 v2, 16, v4
	v_fma_f32 v1, v24, v44, v6
	v_add_f32_e32 v52, v1, v2
	v_fma_f32 v1, v8, v44, v20
	v_and_b32_e32 v2, 0xffff0000, v4
	v_add_f32_e32 v51, v1, v2
	v_fmac_f32_e32 v7, v25, v45
	v_lshlrev_b32_e32 v1, 16, v5
	v_add_f32_e32 v50, v7, v1
	v_and_b32_e32 v1, 0xffff0000, v5
	ds_read2st64_b32 v[4:5], v203 offset0:6 offset1:7
	ds_read2st64_b32 v[6:7], v190 offset0:150 offset1:151
	v_fmac_f32_e32 v21, v9, v45
	ds_read2st64_b32 v[8:9], v190 offset0:166 offset1:167
	v_add_f32_e32 v49, v21, v1
	s_waitcnt lgkmcnt(0)
	v_lshlrev_b32_e32 v2, 16, v4
	v_fma_f32 v1, v26, v46, v6
	v_add_f32_e32 v48, v1, v2
	v_fma_f32 v1, v10, v46, v8
	v_and_b32_e32 v2, 0xffff0000, v4
	v_add_f32_e32 v46, v1, v2
	v_fmac_f32_e32 v7, v27, v47
	v_lshlrev_b32_e32 v1, 16, v5
	v_add_f32_e32 v45, v7, v1
	v_fmac_f32_e32 v9, v11, v47
	v_and_b32_e32 v1, 0xffff0000, v5
	ds_read2st64_b32 v[4:5], v203 offset0:8 offset1:9
	ds_read2st64_b32 v[6:7], v190 offset0:152 offset1:153
	v_add_f32_e32 v44, v9, v1
	ds_read2st64_b32 v[8:9], v190 offset0:168 offset1:169
	s_waitcnt lgkmcnt(0)
	v_lshlrev_b32_e32 v2, 16, v4
	v_fma_f32 v1, v28, v40, v6
	v_add_f32_e32 v27, v1, v2
	v_fma_f32 v1, v12, v40, v8
	v_and_b32_e32 v2, 0xffff0000, v4
	v_add_f32_e32 v26, v1, v2
	v_fmac_f32_e32 v7, v29, v41
	v_lshlrev_b32_e32 v1, 16, v5
	v_add_f32_e32 v25, v7, v1
	v_fmac_f32_e32 v9, v13, v41
	v_and_b32_e32 v1, 0xffff0000, v5
	ds_read2st64_b32 v[4:5], v203 offset0:10 offset1:11
	ds_read2st64_b32 v[6:7], v190 offset0:154 offset1:155
	v_add_f32_e32 v24, v9, v1
	ds_read2st64_b32 v[8:9], v190 offset0:170 offset1:171
	s_waitcnt lgkmcnt(0)
	v_lshlrev_b32_e32 v2, 16, v4
	v_fma_f32 v1, v30, v42, v6
	v_add_f32_e32 v23, v1, v2
	v_fma_f32 v1, v14, v42, v8
	v_and_b32_e32 v2, 0xffff0000, v4
	v_add_f32_e32 v22, v1, v2
	v_fmac_f32_e32 v7, v31, v43
	v_lshlrev_b32_e32 v1, 16, v5
	v_add_f32_e32 v21, v7, v1
	v_fmac_f32_e32 v9, v15, v43
	v_and_b32_e32 v1, 0xffff0000, v5
	ds_read2st64_b32 v[4:5], v203 offset0:12 offset1:13
	ds_read2st64_b32 v[6:7], v190 offset0:156 offset1:157
	v_add_f32_e32 v15, v9, v1
	ds_read2st64_b32 v[8:9], v190 offset0:172 offset1:173
	s_waitcnt lgkmcnt(0)
	v_lshlrev_b32_e32 v2, 16, v4
	v_fma_f32 v1, v32, v36, v6
	v_add_f32_e32 v20, v1, v2
	v_fma_f32 v1, v16, v36, v8
	v_and_b32_e32 v2, 0xffff0000, v4
	v_add_f32_e32 v14, v1, v2
	v_fmac_f32_e32 v7, v33, v37
	v_lshlrev_b32_e32 v1, 16, v5
	v_add_f32_e32 v13, v7, v1
	v_fmac_f32_e32 v9, v17, v37
	v_and_b32_e32 v1, 0xffff0000, v5
	ds_read2st64_b32 v[4:5], v203 offset0:14 offset1:15
	ds_read2st64_b32 v[6:7], v190 offset0:158 offset1:159
	v_add_f32_e32 v12, v9, v1
	ds_read2st64_b32 v[8:9], v190 offset0:174 offset1:175
	s_waitcnt lgkmcnt(0)
	v_lshlrev_b32_e32 v2, 16, v4
	v_fma_f32 v1, v34, v38, v6
	v_add_f32_e32 v10, v1, v2
	v_fma_f32 v1, v18, v38, v8
	v_and_b32_e32 v2, 0xffff0000, v4
	v_add_f32_e32 v11, v1, v2
	v_fmac_f32_e32 v7, v35, v39
	v_lshlrev_b32_e32 v1, 16, v5
	v_add_f32_e32 v2, v7, v1
	v_fmac_f32_e32 v9, v19, v39
	v_and_b32_e32 v1, 0xffff0000, v5
	v_mov_b32_e32 v135, v3
	v_add_f32_e32 v1, v9, v1
	v_lshl_add_u64 v[8:9], s[0:1], 0, v[134:135]
	s_mov_b64 s[0:1], 0xb500000
	v_lshl_add_u64 v[16:17], v[8:9], 0, s[0:1]
	v_lshl_add_u64 v[4:5], v[16:17], 0, v[126:127]
	s_barrier
; #define LAS __attribute__((address_space(3)))
; #define LDS_WAIT() asm volatile("s_waitcnt lgkmcnt(0)" ::: "memory")
; DI unsigned cvtpk(float lo, float hi) { f32x2 v = {lo, hi}; bf16x2_t b = __builtin_convertvector(v, bf16x2_t); return __builtin_bit_cast(unsigned, b); }
; DI float bf2f(bf16 b) { return __uint_as_float(((unsigned)b) << 16); }
; DI float siluf_(float x) { return x / (1.f + __expf(-x)); }
; DI void nsa_unit(const Ctx& c0, int b, int g, int i, LAS unsigned char* lds) {
;     ...
;       for (int it = 0; it < 4; ++it) { const int rw = 8 * it + (lane >> 3), ch = lane & 7;
;           *(LAS u32x4*)(S + rw * 128 + ch * 16) = *(const u32x4*)(nzg + (size_t)rw * 512 + ch * 8); }
;       LDS_WAIT();
; #pragma unroll
;       for (int rg = 0; rg < 16; ++rg) { LAS bf16* e = (LAS bf16*)(S + ((rg & 3) + 8 * (rg >> 2) + 4 * hi) * 128 + r * 2);
;           const float z0 = bf2f(e[0]), z1 = bf2f(e[32]);
;           e[0] = (bf16)(cvtpk(ca0[rg] * siluf_(z0), 0.f) & 0xffffu);
;           e[32] = (bf16)(cvtpk(ca1[rg] * siluf_(z1), 0.f) & 0xffffu); }
	s_add_i32 s25, s25, 1
	s_cmp_eq_u32 s25, 4
	s_waitcnt vmcnt(0) lgkmcnt(0)
	ds_write_b128 v211, v[230:233]
	ds_write_b128 v212, v[234:237]
	ds_write_b128 v213, v[238:241]
	ds_write_b128 v214, v[242:245]
	s_waitcnt lgkmcnt(0)
	ds_read_u16 v4, v215
	ds_read_u16 v5, v215 offset:64
	s_waitcnt lgkmcnt(1)
	v_lshlrev_b32_e32 v4, 16, v4
	v_mul_f32_e32 v6, 0xbfb8aa3b, v4
	v_exp_f32_e32 v6, v6
	s_waitcnt lgkmcnt(0)
	v_lshlrev_b32_e32 v5, 16, v5
	v_add_f32_e32 v6, 1.0, v6
	v_rcp_f32_e32 v7, v6
	s_nop 0
	v_mul_f32_e32 v4, v4, v7
	v_mul_f32_e32 v4, v60, v4
	v_cvt_pk_bf16_f32 v4, v4, v4
	ds_write_b16 v215, v4
	v_mul_f32_e32 v4, 0xbfb8aa3b, v5
	v_exp_f32_e32 v4, v4
	s_nop 0
	v_add_f32_e32 v4, 1.0, v4
	v_rcp_f32_e32 v4, v4
	s_nop 0
	v_mul_f32_e32 v4, v5, v4
	v_mul_f32_e32 v4, v59, v4
	v_cvt_pk_bf16_f32 v4, v4, v4
	ds_write_b16 v215, v4 offset:64
	ds_read_u16 v4, v215 offset:128
	ds_read_u16 v5, v215 offset:192
	s_waitcnt lgkmcnt(1)
	v_lshlrev_b32_e32 v4, 16, v4
	v_mul_f32_e32 v6, 0xbfb8aa3b, v4
	v_exp_f32_e32 v6, v6
	s_waitcnt lgkmcnt(0)
	v_lshlrev_b32_e32 v5, 16, v5
	v_add_f32_e32 v6, 1.0, v6
	v_rcp_f32_e32 v7, v6
	s_nop 0
	v_mul_f32_e32 v4, v4, v7
	v_mul_f32_e32 v4, v58, v4
	v_cvt_pk_bf16_f32 v4, v4, v4
	ds_write_b16 v215, v4 offset:128
	v_mul_f32_e32 v4, 0xbfb8aa3b, v5
	v_exp_f32_e32 v4, v4
	s_nop 0
	v_add_f32_e32 v4, 1.0, v4
	v_rcp_f32_e32 v4, v4
	s_nop 0
	v_mul_f32_e32 v4, v5, v4
	v_mul_f32_e32 v4, v57, v4
	v_cvt_pk_bf16_f32 v4, v4, v4
	ds_write_b16 v215, v4 offset:192
	ds_read_u16 v4, v215 offset:256
	ds_read_u16 v5, v215 offset:320
	s_waitcnt lgkmcnt(1)
	v_lshlrev_b32_e32 v4, 16, v4
	v_mul_f32_e32 v6, 0xbfb8aa3b, v4
	v_exp_f32_e32 v6, v6
	s_waitcnt lgkmcnt(0)
	v_lshlrev_b32_e32 v5, 16, v5
	v_add_f32_e32 v6, 1.0, v6
	v_rcp_f32_e32 v7, v6
	s_nop 0
	v_mul_f32_e32 v4, v4, v7
	v_mul_f32_e32 v4, v56, v4
	v_cvt_pk_bf16_f32 v4, v4, v4
	ds_write_b16 v215, v4 offset:256
	v_mul_f32_e32 v4, 0xbfb8aa3b, v5
	v_exp_f32_e32 v4, v4
	s_nop 0
	v_add_f32_e32 v4, 1.0, v4
	v_rcp_f32_e32 v4, v4
	s_nop 0
	v_mul_f32_e32 v4, v5, v4
	v_mul_f32_e32 v4, v55, v4
	v_cvt_pk_bf16_f32 v4, v4, v4
	ds_write_b16 v215, v4 offset:320
	ds_read_u16 v4, v215 offset:384
	ds_read_u16 v5, v215 offset:448
	s_waitcnt lgkmcnt(1)
	v_lshlrev_b32_e32 v4, 16, v4
	v_mul_f32_e32 v6, 0xbfb8aa3b, v4
	v_exp_f32_e32 v6, v6
	s_waitcnt lgkmcnt(0)
	v_lshlrev_b32_e32 v5, 16, v5
	v_add_f32_e32 v6, 1.0, v6
	v_rcp_f32_e32 v7, v6
	s_nop 0
	v_mul_f32_e32 v4, v4, v7
	v_mul_f32_e32 v4, v54, v4
	v_cvt_pk_bf16_f32 v4, v4, v4
	ds_write_b16 v215, v4 offset:384
	v_mul_f32_e32 v4, 0xbfb8aa3b, v5
	v_exp_f32_e32 v4, v4
	s_nop 0
	v_add_f32_e32 v4, 1.0, v4
	v_rcp_f32_e32 v4, v4
	s_nop 0
	v_mul_f32_e32 v4, v5, v4
	v_mul_f32_e32 v4, v53, v4
	v_cvt_pk_bf16_f32 v4, v4, v4
	ds_write_b16 v215, v4 offset:448
	ds_read_u16 v4, v215 offset:1024
	ds_read_u16 v5, v215 offset:1088
	s_waitcnt lgkmcnt(1)
	v_lshlrev_b32_e32 v4, 16, v4
	v_mul_f32_e32 v6, 0xbfb8aa3b, v4
	v_exp_f32_e32 v6, v6
	s_waitcnt lgkmcnt(0)
	v_lshlrev_b32_e32 v5, 16, v5
	v_add_f32_e32 v6, 1.0, v6
	v_rcp_f32_e32 v7, v6
	s_nop 0
	v_mul_f32_e32 v4, v4, v7
	v_mul_f32_e32 v4, v52, v4
	v_cvt_pk_bf16_f32 v4, v4, v4
	ds_write_b16 v215, v4 offset:1024
	v_mul_f32_e32 v4, 0xbfb8aa3b, v5
	v_exp_f32_e32 v4, v4
	s_nop 0
	v_add_f32_e32 v4, 1.0, v4
	v_rcp_f32_e32 v4, v4
	s_nop 0
	v_mul_f32_e32 v4, v5, v4
	v_mul_f32_e32 v4, v51, v4
	v_cvt_pk_bf16_f32 v4, v4, v4
	ds_write_b16 v215, v4 offset:1088
	ds_read_u16 v4, v215 offset:1152
	ds_read_u16 v5, v215 offset:1216
	s_waitcnt lgkmcnt(1)
	v_lshlrev_b32_e32 v4, 16, v4
	v_mul_f32_e32 v6, 0xbfb8aa3b, v4
	v_exp_f32_e32 v6, v6
	s_waitcnt lgkmcnt(0)
	v_lshlrev_b32_e32 v5, 16, v5
	v_add_f32_e32 v6, 1.0, v6
	v_rcp_f32_e32 v7, v6
	s_nop 0
	v_mul_f32_e32 v4, v4, v7
	v_mul_f32_e32 v4, v50, v4
	v_cvt_pk_bf16_f32 v4, v4, v4
	ds_write_b16 v215, v4 offset:1152
	v_mul_f32_e32 v4, 0xbfb8aa3b, v5
	v_exp_f32_e32 v4, v4
	s_nop 0
	v_add_f32_e32 v4, 1.0, v4
	v_rcp_f32_e32 v4, v4
	s_nop 0
	v_mul_f32_e32 v4, v5, v4
	v_mul_f32_e32 v4, v49, v4
	v_cvt_pk_bf16_f32 v4, v4, v4
	ds_write_b16 v215, v4 offset:1216
	ds_read_u16 v4, v215 offset:1280
	ds_read_u16 v5, v215 offset:1344
	s_waitcnt lgkmcnt(1)
	v_lshlrev_b32_e32 v4, 16, v4
	v_mul_f32_e32 v6, 0xbfb8aa3b, v4
	v_exp_f32_e32 v6, v6
	s_waitcnt lgkmcnt(0)
	v_lshlrev_b32_e32 v5, 16, v5
	v_add_f32_e32 v6, 1.0, v6
	v_rcp_f32_e32 v7, v6
	s_nop 0
	v_mul_f32_e32 v4, v4, v7
	v_mul_f32_e32 v4, v48, v4
	v_cvt_pk_bf16_f32 v4, v4, v4
	ds_write_b16 v215, v4 offset:1280
	v_mul_f32_e32 v4, 0xbfb8aa3b, v5
	v_exp_f32_e32 v4, v4
	s_nop 0
	v_add_f32_e32 v4, 1.0, v4
	v_rcp_f32_e32 v4, v4
	s_nop 0
	v_mul_f32_e32 v4, v5, v4
	v_mul_f32_e32 v4, v46, v4
	v_cvt_pk_bf16_f32 v4, v4, v4
	ds_write_b16 v215, v4 offset:1344
	ds_read_u16 v4, v215 offset:1408
	s_waitcnt lgkmcnt(0)
	v_lshlrev_b32_e32 v5, 16, v4
	v_mul_f32_e32 v6, 0xbfb8aa3b, v5
	v_exp_f32_e32 v6, v6
	ds_read_u16 v4, v215 offset:1472
	v_add_f32_e32 v6, 1.0, v6
	v_div_scale_f32 v7, s[0:1], v6, v6, v5
	s_waitcnt lgkmcnt(0)
	v_lshlrev_b32_e32 v4, 16, v4
	v_rcp_f32_e32 v7, v6
	s_nop 0
	v_mul_f32_e32 v5, v5, v7
	v_mul_f32_e32 v5, v45, v5
	v_cvt_pk_bf16_f32 v5, v5, s0
	ds_write_b16 v215, v5 offset:1408
	v_mul_f32_e32 v5, 0xbfb8aa3b, v4
	v_exp_f32_e32 v5, v5
	s_nop 0
	v_add_f32_e32 v5, 1.0, v5
	v_rcp_f32_e32 v6, v5
	s_nop 0
	v_mul_f32_e32 v4, v4, v6
	v_mul_f32_e32 v4, v44, v4
	v_cvt_pk_bf16_f32 v4, v4, v4
	ds_write_b16 v215, v4 offset:1472
	ds_read_u16 v4, v215 offset:2048
	ds_read_u16 v5, v215 offset:2112
	s_waitcnt lgkmcnt(1)
	v_lshlrev_b32_e32 v4, 16, v4
	v_mul_f32_e32 v6, 0xbfb8aa3b, v4
	v_exp_f32_e32 v6, v6
	s_waitcnt lgkmcnt(0)
; #define LAS __attribute__((address_space(3)))
; #define LDS_WAIT() asm volatile("s_waitcnt lgkmcnt(0)" ::: "memory")
; DI unsigned cvtpk(float lo, float hi) { f32x2 v = {lo, hi}; bf16x2_t b = __builtin_convertvector(v, bf16x2_t); return __builtin_bit_cast(unsigned, b); }
; DI float bf2f(bf16 b) { return __uint_as_float(((unsigned)b) << 16); }
; DI float siluf_(float x) { return x / (1.f + __expf(-x)); }
; DI void nsa_unit(const Ctx& c0, int b, int g, int i, LAS unsigned char* lds) {
;     ...
;       for (int rg = 0; rg < 16; ++rg) { LAS bf16* e = (LAS bf16*)(S + ((rg & 3) + 8 * (rg >> 2) + 4 * hi) * 128 + r * 2);
;           const float z0 = bf2f(e[0]), z1 = bf2f(e[32]);
;           e[0] = (bf16)(cvtpk(ca0[rg] * siluf_(z0), 0.f) & 0xffffu);
;           e[32] = (bf16)(cvtpk(ca1[rg] * siluf_(z1), 0.f) & 0xffffu); }
;       LDS_WAIT();
; #pragma unroll
;       for (int it = 0; it < 4; ++it) { const int rw = 8 * it + (lane >> 3), ch = lane & 7;
;           *(u32x4*)(ong + (size_t)rw * 512 + ch * 8) = *(const LAS u32x4*)(S + rw * 128 + ch * 16); }
;       LDS_WAIT(); }
	v_lshlrev_b32_e32 v5, 16, v5
	v_add_f32_e32 v6, 1.0, v6
	v_rcp_f32_e32 v7, v6
	s_nop 0
	v_mul_f32_e32 v4, v4, v7
	v_mul_f32_e32 v4, v27, v4
	v_cvt_pk_bf16_f32 v4, v4, v4
	ds_write_b16 v215, v4 offset:2048
	v_mul_f32_e32 v4, 0xbfb8aa3b, v5
	v_exp_f32_e32 v4, v4
	s_nop 0
	v_add_f32_e32 v4, 1.0, v4
	v_rcp_f32_e32 v4, v4
	s_nop 0
	v_mul_f32_e32 v4, v5, v4
	v_mul_f32_e32 v4, v26, v4
	v_cvt_pk_bf16_f32 v4, v4, v4
	ds_write_b16 v215, v4 offset:2112
	ds_read_u16 v4, v215 offset:2176
	ds_read_u16 v5, v215 offset:2240
	s_waitcnt lgkmcnt(1)
	v_lshlrev_b32_e32 v4, 16, v4
	v_mul_f32_e32 v6, 0xbfb8aa3b, v4
	v_exp_f32_e32 v6, v6
	s_waitcnt lgkmcnt(0)
	v_lshlrev_b32_e32 v5, 16, v5
	v_add_f32_e32 v6, 1.0, v6
	v_rcp_f32_e32 v7, v6
	s_nop 0
	v_mul_f32_e32 v4, v4, v7
	v_mul_f32_e32 v4, v25, v4
	v_cvt_pk_bf16_f32 v4, v4, v4
	ds_write_b16 v215, v4 offset:2176
	v_mul_f32_e32 v4, 0xbfb8aa3b, v5
	v_exp_f32_e32 v4, v4
	s_nop 0
	v_add_f32_e32 v4, 1.0, v4
	v_rcp_f32_e32 v4, v4
	s_nop 0
	v_mul_f32_e32 v4, v5, v4
	v_mul_f32_e32 v4, v24, v4
	v_cvt_pk_bf16_f32 v4, v4, v4
	ds_write_b16 v215, v4 offset:2240
	ds_read_u16 v4, v215 offset:2304
	ds_read_u16 v5, v215 offset:2368
	s_waitcnt lgkmcnt(1)
	v_lshlrev_b32_e32 v4, 16, v4
	v_mul_f32_e32 v6, 0xbfb8aa3b, v4
	v_exp_f32_e32 v6, v6
	s_waitcnt lgkmcnt(0)
	v_lshlrev_b32_e32 v5, 16, v5
	v_add_f32_e32 v6, 1.0, v6
	v_rcp_f32_e32 v7, v6
	s_nop 0
	v_mul_f32_e32 v4, v4, v7
	v_mul_f32_e32 v4, v23, v4
	v_cvt_pk_bf16_f32 v4, v4, v4
	ds_write_b16 v215, v4 offset:2304
	v_mul_f32_e32 v4, 0xbfb8aa3b, v5
	v_exp_f32_e32 v4, v4
	s_nop 0
	v_add_f32_e32 v4, 1.0, v4
	v_rcp_f32_e32 v4, v4
	s_nop 0
	v_mul_f32_e32 v4, v5, v4
	v_mul_f32_e32 v4, v22, v4
	v_cvt_pk_bf16_f32 v4, v4, v4
	ds_write_b16 v215, v4 offset:2368
	ds_read_u16 v4, v215 offset:2432
	ds_read_u16 v5, v215 offset:2496
	s_waitcnt lgkmcnt(1)
	v_lshlrev_b32_e32 v4, 16, v4
	v_mul_f32_e32 v6, 0xbfb8aa3b, v4
	v_exp_f32_e32 v6, v6
	s_waitcnt lgkmcnt(0)
	v_lshlrev_b32_e32 v5, 16, v5
	v_add_f32_e32 v6, 1.0, v6
	v_rcp_f32_e32 v7, v6
	s_nop 0
	v_mul_f32_e32 v4, v4, v7
	v_mul_f32_e32 v4, v21, v4
	v_cvt_pk_bf16_f32 v4, v4, v4
	ds_write_b16 v215, v4 offset:2432
	v_mul_f32_e32 v4, 0xbfb8aa3b, v5
	v_exp_f32_e32 v4, v4
	s_nop 0
	v_add_f32_e32 v4, 1.0, v4
	v_rcp_f32_e32 v4, v4
	s_nop 0
	v_mul_f32_e32 v4, v5, v4
	v_mul_f32_e32 v4, v15, v4
	v_cvt_pk_bf16_f32 v4, v4, v4
	ds_write_b16 v215, v4 offset:2496
	ds_read_u16 v4, v215 offset:3072
	ds_read_u16 v5, v215 offset:3136
	s_waitcnt lgkmcnt(1)
	v_lshlrev_b32_e32 v4, 16, v4
	v_mul_f32_e32 v6, 0xbfb8aa3b, v4
	v_exp_f32_e32 v6, v6
	s_waitcnt lgkmcnt(0)
	v_lshlrev_b32_e32 v5, 16, v5
	v_add_f32_e32 v6, 1.0, v6
	v_rcp_f32_e32 v7, v6
	s_nop 0
	v_mul_f32_e32 v4, v4, v7
	v_mul_f32_e32 v4, v20, v4
	v_cvt_pk_bf16_f32 v4, v4, v4
	ds_write_b16 v215, v4 offset:3072
	v_mul_f32_e32 v4, 0xbfb8aa3b, v5
	v_exp_f32_e32 v4, v4
	s_nop 0
	v_add_f32_e32 v4, 1.0, v4
	v_rcp_f32_e32 v4, v4
	s_nop 0
	v_mul_f32_e32 v4, v5, v4
	v_mul_f32_e32 v4, v14, v4
	v_cvt_pk_bf16_f32 v4, v4, v4
	ds_write_b16 v215, v4 offset:3136
	ds_read_u16 v4, v215 offset:3200
	ds_read_u16 v5, v215 offset:3264
	s_waitcnt lgkmcnt(1)
	v_lshlrev_b32_e32 v4, 16, v4
	v_mul_f32_e32 v6, 0xbfb8aa3b, v4
	v_exp_f32_e32 v6, v6
	s_waitcnt lgkmcnt(0)
	v_lshlrev_b32_e32 v5, 16, v5
	v_add_f32_e32 v6, 1.0, v6
	v_rcp_f32_e32 v7, v6
	s_nop 0
	v_mul_f32_e32 v4, v4, v7
	v_mul_f32_e32 v4, v13, v4
	v_cvt_pk_bf16_f32 v4, v4, v4
	ds_write_b16 v215, v4 offset:3200
	v_mul_f32_e32 v4, 0xbfb8aa3b, v5
	v_exp_f32_e32 v4, v4
	s_nop 0
	v_add_f32_e32 v4, 1.0, v4
	v_rcp_f32_e32 v4, v4
	s_nop 0
	v_mul_f32_e32 v4, v5, v4
	v_mul_f32_e32 v4, v12, v4
	v_cvt_pk_bf16_f32 v4, v4, v4
	ds_write_b16 v215, v4 offset:3264
	ds_read_u16 v4, v215 offset:3328
	ds_read_u16 v5, v215 offset:3392
	s_waitcnt lgkmcnt(1)
	v_lshlrev_b32_e32 v4, 16, v4
	v_mul_f32_e32 v6, 0xbfb8aa3b, v4
	v_exp_f32_e32 v6, v6
	s_waitcnt lgkmcnt(0)
	v_lshlrev_b32_e32 v5, 16, v5
	v_add_f32_e32 v6, 1.0, v6
	v_rcp_f32_e32 v7, v6
	s_nop 0
	v_mul_f32_e32 v4, v4, v7
	v_mul_f32_e32 v4, v10, v4
	v_cvt_pk_bf16_f32 v4, v4, v4
	ds_write_b16 v215, v4 offset:3328
	v_mul_f32_e32 v4, 0xbfb8aa3b, v5
	v_exp_f32_e32 v4, v4
	s_nop 0
	v_add_f32_e32 v4, 1.0, v4
	v_rcp_f32_e32 v4, v4
	s_nop 0
	v_mul_f32_e32 v4, v5, v4
	v_mul_f32_e32 v4, v11, v4
	v_cvt_pk_bf16_f32 v4, v4, v4
	ds_write_b16 v215, v4 offset:3392
	ds_read_u16 v4, v215 offset:3456
	ds_read_u16 v5, v215 offset:3520
	s_waitcnt lgkmcnt(1)
	v_lshlrev_b32_e32 v4, 16, v4
	v_mul_f32_e32 v6, 0xbfb8aa3b, v4
	v_exp_f32_e32 v6, v6
	s_waitcnt lgkmcnt(0)
	v_lshlrev_b32_e32 v5, 16, v5
	v_add_f32_e32 v6, 1.0, v6
	v_div_scale_f32 v7, s[0:1], v6, v6, v4
	s_nop 0
	v_rcp_f32_e32 v7, v6
	s_nop 0
	v_mul_f32_e32 v4, v4, v7
	v_mul_f32_e32 v2, v2, v4
	v_cvt_pk_bf16_f32 v2, v2, s0
	ds_write_b16 v215, v2 offset:3456
	v_mul_f32_e32 v2, 0xbfb8aa3b, v5
	v_exp_f32_e32 v2, v2
	s_nop 0
	v_add_f32_e32 v2, 1.0, v2
	v_div_scale_f32 v4, s[0:1], v2, v2, v5
	s_nop 0
	v_rcp_f32_e32 v2, v2
	s_nop 0
	v_mul_f32_e32 v2, v5, v2
	v_mul_f32_e32 v1, v1, v2
	v_cvt_pk_bf16_f32 v1, v1, s0
	ds_write_b16 v215, v1 offset:3520
	s_waitcnt lgkmcnt(0)
	ds_read_b128 v[4:7], v211
	s_mov_b64 s[0:1], 0xd500000
	v_lshl_add_u64 v[8:9], v[8:9], 0, s[0:1]
	v_lshl_add_u64 v[10:11], v[8:9], 0, v[126:127]
	s_waitcnt lgkmcnt(0)
	global_store_dwordx4 v[10:11], v[4:7], off
	ds_read_b128 v[4:7], v212
	v_lshl_add_u64 v[10:11], v[8:9], 0, v[128:129]
	s_waitcnt lgkmcnt(0)
	global_store_dwordx4 v[10:11], v[4:7], off
	ds_read_b128 v[4:7], v213
	v_lshl_add_u64 v[10:11], v[8:9], 0, v[130:131]
	v_lshl_add_u64 v[8:9], v[8:9], 0, v[132:133]
	s_waitcnt lgkmcnt(0)
	global_store_dwordx4 v[10:11], v[4:7], off
	ds_read_b128 v[4:7], v214
	s_waitcnt lgkmcnt(0)
	global_store_dwordx4 v[8:9], v[4:7], off
	s_waitcnt lgkmcnt(0)
	s_cbranch_scc1 .LBB0_1151
